# weight transposes (all but w_in[0]) moved out of the prologue into the RWKV loader waves during M2: per-wave item tables decoded once with VALU, one half-item (32x32) per 16-step interval, dwordx4 loa
# speedup vs baseline: 1.0222x; 1.0222x over previous
; #define LAS __attribute__((address_space(3)))
; #define GAS __attribute__((address_space(1)))
; __device__ __forceinline__ void p0_prologue(ArgP A, LAS unsigned char* lds, int tid, int lane, int wave, int bid, int G) {
;     LAS float* scr = (LAS float*)(lds + wave * 16384);
;     const int gw = bid * NWAVES + wave, NGW = G * NWAVES;
;     constexpr int I_IN = 32 * 165, I_OUT = 32 * 64, I_GU = 32 * 352, I_DN = 88 * 64, I_GT = 32 * 64, I_PL = 4 * 64, I_L = I_IN + I_OUT + I_GU + I_DN + I_GT + I_PL;
;     for (int it = gw; it < 2 * I_L; it += NGW) {
;         const int layer = it / I_L; int r = it - layer * I_L;
;         GAS unsigned char* wb = A->ws + (size_t)layer * WL_BYTES;
;         if (r < I_IN) { p0_transpose_item(A->in[12] + (size_t)layer * DM * 5280, DM, 5280, (GAS bf16*)(wb + WO_IN), 0 | (layer ? 2 : 0), scr, r, lane); continue; } r -= I_IN;
;         if (r < I_OUT) { p0_transpose_item(A->in[33] + (size_t)layer * DM * DM, DM, DM, (GAS bf16*)(wb + WO_OUT), 0 | (layer ? 2 : 0), scr, r, lane); continue; } r -= I_OUT;
;         if (r < I_GU) { p0_transpose_item(A->in[34] + (size_t)layer * DM * 2 * DFF, DM, 2 * DFF, (GAS bf16*)(wb + WO_GU), 1 | (layer ? 2 : 0), scr, r, lane); continue; } r -= I_GU;
;         if (r < I_DN) { p0_transpose_item(A->in[35] + (size_t)layer * DFF * DM, DFF, DM, (GAS bf16*)(wb + WO_DN), 0 | (layer ? 2 : 0), scr, r, lane); continue; } r -= I_DN;
;         if (r < I_GT) { p0_transpose_item(A->in[36] + (size_t)layer * DM * DM, DM, DM, (GAS bf16*)(wb + WO_GT), 0 | (layer ? 2 : 0), scr, r, lane); continue; } r -= I_GT;
;         p0_transpose_item(A->in[37] + (size_t)layer * PLED * DM, PLED, DM, (GAS bf16*)(wb + WO_PL), 0 | (layer ? 2 : 0), scr, r, lane);
;     }
.LBB0_5:
	s_or_b64 exec, exec, s[2:3]
	s_mov_b64 s[2:3], s[68:69]
	s_load_dwordx2 s[74:75], s[2:3], 0x140
	v_writelane_b32 v251, s68, 2
	s_waitcnt lgkmcnt(0)
	s_cmp_lt_i32 s74, 1
	v_writelane_b32 v251, s69, 3
	v_writelane_b32 v251, s70, 4
	s_cselect_b64 s[8:9], -1, 0
	s_cmp_gt_i32 s75, 0
	v_writelane_b32 v251, s72, 5
	s_cselect_b64 s[2:3], -1, 0
	s_and_b64 s[2:3], s[8:9], s[2:3]
	v_writelane_b32 v251, s73, 6
	v_writelane_b32 v251, s74, 7
	s_andn2_b64 vcc, exec, s[2:3]
	s_nop 0
	v_writelane_b32 v251, s75, 8
	s_cbranch_vccnz .LBB0_42
	v_mov_b32_e32 v1, v195
	s_lshl_b32 s3, s70, 3
	v_readfirstlane_b32 s2, v1
	s_ashr_i32 s2, s2, 6
	v_and_b32_e32 v6, 63, v1
	s_add_i32 s10, s2, s3
	s_lshl_b32 s12, s92, 3
	s_cmp_gt_i32 s10, 0x149f
	s_mov_b64 s[16:17], s[68:69]
	v_lshlrev_b32_e32 v8, 3, v6
	s_cbranch_scc1 .LBB0_33
	s_lshl_b32 s3, s2, 14
	v_lshrrev_b32_e32 v7, 5, v6
	v_and_b32_e32 v2, 31, v1
	s_add_i32 s3, s3, 0
	v_lshlrev_b32_e32 v4, 2, v2
	v_mul_u32_u24_e32 v5, 0x84, v7
	v_add3_u32 v9, s3, v4, v5
	v_lshrrev_b32_e32 v10, 3, v6
	v_and_b32_e32 v4, 56, v8
	s_load_dwordx2 s[18:19], s[16:17], 0x138
	v_mul_u32_u24_e32 v5, 0x84, v4
	v_lshlrev_b32_e32 v11, 2, v10
	v_add3_u32 v11, s3, v5, v11
	v_readlane_b32 s3, v251, 4
	s_lshl_b32 s3, s3, 8
	s_lshl_b32 s2, s2, 5
	s_mov_b32 s5, 0
	v_mov_b32_e32 v3, 0
	v_or_b32_e32 v12, 8, v10
	v_or_b32_e32 v13, 16, v10
	v_or_b32_e32 v14, 24, v10
	s_add_i32 s11, s3, s2
	s_lshl_b32 s13, s92, 8
	s_movk_i32 s22, 0x4000
	s_mov_b32 s23, 0x8000
	s_mov_b32 s34, 0xc000
	s_mov_b32 s35, 0x10000
	s_mov_b32 s36, 0x14000
	s_mov_b32 s37, 0x18000
	s_mov_b32 s38, 0x1c000
	s_mov_b32 s39, 0x20000
	s_mov_b32 s40, 0x24000
	s_mov_b32 s41, 0x28000
	s_mov_b32 s42, 0x2c000
	s_mov_b32 s43, 0x30000
	s_mov_b32 s44, 0x34000
	s_mov_b32 s45, 0x38000
	s_mov_b32 s46, 0x3c000
	s_mov_b32 s47, 0x40000
	s_mov_b32 s48, 0x44000
	s_mov_b32 s49, 0x48000
	s_mov_b32 s51, 0x4c000
	s_mov_b32 s52, 0x50000
	s_mov_b32 s53, 0x54000
	s_mov_b32 s54, 0x58000
	s_mov_b32 s55, 0x5c000
	s_mov_b32 s56, 0x60000
	s_mov_b32 s57, 0x64000
	s_mov_b32 s58, 0x68000
	s_mov_b32 s59, 0x6c000
	s_mov_b32 s60, 0x70000
	s_mov_b32 s61, 0x74000
	s_mov_b32 s62, 0x78000
	s_mov_b32 s63, 0x7c000
	s_mov_b32 s64, 0x11e000
	s_mov_b32 s65, 0x134000
	s_mov_b32 s66, 0x14a000
	s_mov_b32 s67, 0x160000
	s_mov_b32 s68, 0x176000
	s_mov_b32 s69, 0x18c000
	s_mov_b32 s70, 0x1a2000
	s_mov_b32 s71, 0x1b8000
	s_mov_b32 s72, 0x1ce000
	s_mov_b32 s73, 0x1e4000
	s_mov_b32 s74, 0x1fa000
	s_mov_b32 s75, 0x210000
	s_mov_b32 s76, 0x226000
	s_mov_b32 s77, 0x23c000
	s_mov_b32 s78, 0x252000
	s_mov_b32 s79, 0x268000
	s_mov_b32 s80, 0x27e000
	s_mov_b32 s81, 0x294000
	s_mov_b32 s82, 0x2aa000
	s_movk_i32 s83, 0x5280
	v_lshlrev_b32_e32 v2, 2, v2
	v_add_u32_e32 v15, 0x400, v9
	v_add_u32_e32 v16, 0x800, v9
	v_add_u32_e32 v17, 0xc00, v9
	v_add_u32_e32 v18, 0x1000, v9
	v_add_u32_e32 v19, 0x1400, v9
	v_add_u32_e32 v20, 0x1800, v9
	v_add_u32_e32 v21, 0x1c00, v9
	v_lshlrev_b32_e32 v4, 1, v4
	s_mov_b32 s84, s10
	s_mov_b64 s[20:21], 0x5f00000
	s_mov_b64 s[24:25], 0x4900000
	s_mov_b64 s[26:27], 0x1d00000
	s_mov_b64 s[28:29], 0x1500000
	s_branch .LBB0_9
.LBB0_8:
	s_add_i32 s84, s84, s12
	s_add_i32 s11, s11, s13
	s_cmp_gt_i32 s84, 0x149f
	s_cbranch_scc1 .LBB0_33

; #define LAS __attribute__((address_space(3)))
; #define GAS __attribute__((address_space(1)))
; __device__ __forceinline__ void p0_transpose_item(const GAS float* W, int K, int N, GAS bf16* WT, int mode, LAS float* scr, int item, int lane) {
;     const int nblk = N / 32, kb = item / nblk, nb = item % nblk, k0 = 64 * kb, n0 = 32 * nb;
;     int r0 = n0;
;     if (mode & 1) { r0 = (n0 < DFF) ? (n0 / 128) * 256 + (n0 % 128) : ((n0 - DFF) / 128) * 256 + 128 + ((n0 - DFF) % 128); }
; __device__ __forceinline__ void p0_prologue(ArgP A, LAS unsigned char* lds, int tid, int lane, int wave, int bid, int G) {
;     ...
;     constexpr int I_IN = 32 * 165, I_OUT = 32 * 64, I_GU = 32 * 352, I_DN = 88 * 64, I_GT = 32 * 64, I_PL = 4 * 64, I_L = I_IN + I_OUT + I_GU + I_DN + I_GT + I_PL;
;     for (int it = gw; it < 2 * I_L; it += NGW) {
;         const int layer = it / I_L; int r = it - layer * I_L;
;         GAS unsigned char* wb = A->ws + (size_t)layer * WL_BYTES;
;         if (r < I_IN) { p0_transpose_item(A->in[12] + (size_t)layer * DM * 5280, DM, 5280, (GAS bf16*)(wb + WO_IN), 0 | (layer ? 2 : 0), scr, r, lane); continue; } r -= I_IN;
;         if (r < I_OUT) { p0_transpose_item(A->in[33] + (size_t)layer * DM * DM, DM, DM, (GAS bf16*)(wb + WO_OUT), 0 | (layer ? 2 : 0), scr, r, lane); continue; } r -= I_OUT;
;         if (r < I_GU) { p0_transpose_item(A->in[34] + (size_t)layer * DM * 2 * DFF, DM, 2 * DFF, (GAS bf16*)(wb + WO_GU), 1 | (layer ? 2 : 0), scr, r, lane); continue; } r -= I_GU;
;         if (r < I_DN) { p0_transpose_item(A->in[35] + (size_t)layer * DFF * DM, DFF, DM, (GAS bf16*)(wb + WO_DN), 0 | (layer ? 2 : 0), scr, r, lane); continue; } r -= I_DN;
;         if (r < I_GT) { p0_transpose_item(A->in[36] + (size_t)layer * DM * DM, DM, DM, (GAS bf16*)(wb + WO_GT), 0 | (layer ? 2 : 0), scr, r, lane); continue; } r -= I_GT;
;         p0_transpose_item(A->in[37] + (size_t)layer * PLED * DM, PLED, DM, (GAS bf16*)(wb + WO_PL), 0 | (layer ? 2 : 0), scr, r, lane);
.Lld_entry:
	s_cmp_lt_u32 s24, 4
	s_cbranch_scc1 .LBB0_709
	v_readlane_b32 s0, v251, 4
	s_load_dwordx2 s[6:7], s[68:69], 0x138
	s_nop 3
	s_sub_u32 s1, s24, 4
	s_lshl_b32 s2, s0, 2
	s_lshr_b32 s3, s2, 7
	s_bfe_u32 s12, s2, 0x30004
	v_and_b32_e32 v0, 63, v195
	v_lshlrev_b32_e32 v0, 2, v0
	s_lshl_b32 s16, s1, 8
	v_add_u32_e32 v1, s16, v0
	v_lshrrev_b32_e32 v2, 7, v1
	v_mul_u32_u24_e32 v3, 11, v2
	v_lshrrev_b32_e32 v3, 5, v3
	v_mul_u32_u24_e32 v4, 0x180, v3
	v_sub_u32_e32 v4, v1, v4
	v_lshrrev_b32_e32 v5, 6, v4
	v_and_b32_e32 v6, 63, v4
	v_lshlrev_b32_e32 v6, 2, v6
	v_lshl_add_u32 v6, v3, 11, v6
	s_mov_b32 s8, 0x1100000
	v_mul_lo_u32 v5, v5, s8
	v_add_u32_e32 v20, v5, v6
	v_add_u32_e32 v1, 0x400, v1
	v_lshrrev_b32_e32 v2, 7, v1
	v_mul_u32_u24_e32 v3, 11, v2
	v_lshrrev_b32_e32 v3, 5, v3
	v_mul_u32_u24_e32 v4, 0x180, v3
	v_sub_u32_e32 v4, v1, v4
	v_lshrrev_b32_e32 v5, 6, v4
	v_and_b32_e32 v6, 63, v4
	v_lshlrev_b32_e32 v6, 2, v6
	v_lshl_add_u32 v6, v3, 11, v6
	s_mov_b32 s8, 0x1100000
	v_mul_lo_u32 v5, v5, s8
	v_add_u32_e32 v21, v5, v6
	s_waitcnt lgkmcnt(0)
	s_add_u32 s4, s6, 0x1ad00000
	s_addc_u32 s5, s7, 0
	s_lshl_b32 s3, s3, 22
	s_add_u32 s4, s4, s3
	s_addc_u32 s5, s5, 0
	s_lshl_b32 s12, s12, 8
	s_add_u32 s4, s4, s12
	s_addc_u32 s5, s5, 0
	s_lshl_b32 s16, s1, 10
	s_and_b32 s23, s0, 3
	s_lshl_b32 s23, s23, 2
	s_or_b32 s23, s23, s1
	s_lshl_b32 s23, s23, 4
	s_add_u32 s98, s4, 0x8800000
	s_addc_u32 s99, s5, 0
	s_add_u32 s98, s98, s23
	s_addc_u32 s99, s99, 0
	s_lshl_b32 s25, s1, 13
	s_add_i32 s25, s25, 0x18000
	v_and_b32_e32 v22, 63, v195
	v_and_b32_e32 v23, 15, v22
	v_lshrrev_b32_e32 v24, 4, v22
	v_lshl_add_u32 v25, v22, 2, s25
	v_lshlrev_b32_e32 v27, 11, v23
	v_lshl_add_u32 v27, v24, 2, v27
	s_lshl_b32 s2, s1, 12
	s_add_i32 s2, s2, 0x20000
	s_cmp_eq_u32 s1, 3
	s_cselect_b32 s2, 0x24000, s2
	v_lshrrev_b32_e32 v9, 3, v22
	v_and_b32_e32 v2, 7, v22
	v_lshlrev_b32_e32 v15, 4, v2
	v_lshlrev_b32_e32 v10, 2, v22
	v_lshlrev_b32_e32 v3, 5, v9
	v_lshlrev_b32_e32 v2, 2, v2
	v_add_lshl_u32 v11, v2, v3, 2
	v_add_u32_e32 v11, s2, v11
	v_xor_b32_e32 v4, 8, v2
	v_add_lshl_u32 v12, v4, v3, 2
	v_add_u32_e32 v12, s2, v12
	v_xor_b32_e32 v4, 16, v2
	v_add_lshl_u32 v13, v4, v3, 2
	v_add_u32_e32 v13, s2, v13
	v_xor_b32_e32 v4, 24, v2
	v_add_lshl_u32 v14, v4, v3, 2
	v_add_u32_e32 v14, s2, v14
	v_and_b32_e32 v3, 3, v22
	v_lshrrev_b32_e32 v29, 2, v22
	v_lshlrev_b32_e32 v30, 4, v3
	v_lshlrev_b32_e32 v4, 3, v3
	v_lshlrev_b32_e32 v5, 8, v3
	v_xor_b32_e32 v6, v29, v4
	v_add_lshl_u32 v18, v6, v5, 2
	v_add_u32_e32 v18, s2, v18
	v_add_u32_e32 v6, 16, v29
	v_xor_b32_e32 v6, v6, v4
	v_add_lshl_u32 v19, v6, v5, 2
	v_add_u32_e32 v19, s2, v19
	s_load_dwordx2 s[28:29], s[68:69], 0x60
	s_load_dwordx2 s[30:31], s[68:69], 0x108
	s_load_dwordx2 s[32:33], s[68:69], 0x110
	s_load_dwordx2 s[44:45], s[68:69], 0x118
	s_load_dwordx2 s[62:63], s[68:69], 0x120
	s_load_dwordx2 s[18:19], s[68:69], 0x128
	v_readlane_b32 s8, v254, 10
	s_lshl_b32 s2, s0, 2
	s_add_u32 s2, s2, s1
	s_movk_i32 s3, 0x2940
	s_mov_b32 s9, 0xf880
	s_cmp_eq_u32 s8, 0
	s_cbranch_scc1 .Lxp_l0
	s_mov_b32 s3, 0xf880
	s_mov_b32 s9, 0x19e80
.Lxp_l0:
	s_add_u32 s2, s2, s3
	s_mov_b32 s12, 0
	s_cmp_ge_u32 s2, s9
	s_cbranch_scc1 .Lxp_cnt
	s_sub_u32 s12, s9, s2
	s_sub_u32 s12, s12, 1
	s_lshr_b32 s12, s12, 9
	s_add_u32 s12, s12, 1
.Lxp_cnt:
	s_waitcnt lgkmcnt(0)
	v_add_u32_e32 v1, 0, v22
	v_lshl_add_u32 v1, v1, 9, s2
	v_and_b32_e32 v2, 1, v1
	v_lshrrev_b32_e32 v1, 1, v1
	s_movk_i32 s24, 0x67a0
	v_cmp_le_u32_e32 vcc, s24, v1
	v_cndmask_b32_e64 v3, 0, 1, vcc
	v_mul_u32_u24_e32 v4, 0x67a0, v3
	v_sub_u32_e32 v4, v1, v4
	v_mov_b32_e32 v5, 0
	v_mov_b32_e32 v100, 0x14a0
	v_mov_b32_e32 v101, 0x800
	v_mov_b32_e32 v6, 0x2940000
	v_mov_b32_e32 v7, 0x0
	v_mov_b32_e32 v96, s28
	v_mov_b32_e32 v97, s29
	s_movk_i32 s24, 0x14a0
	v_cmp_le_u32_e32 vcc, s24, v4
	v_mov_b32_e32 v31, 0x14a0
	v_cndmask_b32_e32 v5, v5, v31, vcc
	v_mov_b32_e32 v31, 0x800
	v_cndmask_b32_e32 v100, v100, v31, vcc
	v_mov_b32_e32 v31, 0x800
	v_cndmask_b32_e32 v101, v101, v31, vcc
	v_mov_b32_e32 v31, 0x1000000
	v_cndmask_b32_e32 v6, v6, v31, vcc
	v_mov_b32_e32 v31, 0x1500000
	v_cndmask_b32_e32 v7, v7, v31, vcc
	v_mov_b32_e32 v31, s30
	v_cndmask_b32_e32 v96, v96, v31, vcc
	v_mov_b32_e32 v31, s31
	v_cndmask_b32_e32 v97, v97, v31, vcc
	s_movk_i32 s24, 0x1ca0
	v_cmp_le_u32_e32 vcc, s24, v4
	v_mov_b32_e32 v31, 0x1ca0
	v_cndmask_b32_e32 v5, v5, v31, vcc
	v_mov_b32_e32 v31, 0x2c00
	v_cndmask_b32_e32 v100, v100, v31, vcc
	v_mov_b32_e32 v31, 0x800
	v_cndmask_b32_e32 v101, v101, v31, vcc
	v_mov_b32_e32 v31, 0x5800000
	v_cndmask_b32_e32 v6, v6, v31, vcc
	v_mov_b32_e32 v31, 0x1d00000
	v_cndmask_b32_e32 v7, v7, v31, vcc
	v_mov_b32_e32 v31, s32
	v_cndmask_b32_e32 v96, v96, v31, vcc
	v_mov_b32_e32 v31, s33
	v_cndmask_b32_e32 v97, v97, v31, vcc
	s_movk_i32 s24, 0x48a0
	v_cmp_le_u32_e32 vcc, s24, v4
	v_mov_b32_e32 v31, 0x48a0
	v_cndmask_b32_e32 v5, v5, v31, vcc
	v_mov_b32_e32 v31, 0x800
	v_cndmask_b32_e32 v100, v100, v31, vcc
	v_mov_b32_e32 v31, 0x1600
	v_cndmask_b32_e32 v101, v101, v31, vcc
	v_mov_b32_e32 v31, 0x2c00000
	v_cndmask_b32_e32 v6, v6, v31, vcc
	v_mov_b32_e32 v31, 0x4900000
	v_cndmask_b32_e32 v7, v7, v31, vcc
	v_mov_b32_e32 v31, s44
	v_cndmask_b32_e32 v96, v96, v31, vcc
	v_mov_b32_e32 v31, s45
	v_cndmask_b32_e32 v97, v97, v31, vcc
	s_movk_i32 s24, 0x5ea0
	v_cmp_le_u32_e32 vcc, s24, v4
	v_mov_b32_e32 v31, 0x5ea0
	v_cndmask_b32_e32 v5, v5, v31, vcc
	v_mov_b32_e32 v31, 0x800
	v_cndmask_b32_e32 v100, v100, v31, vcc
	v_mov_b32_e32 v31, 0x800
	v_cndmask_b32_e32 v101, v101, v31, vcc
	v_mov_b32_e32 v31, 0x1000000
	v_cndmask_b32_e32 v6, v6, v31, vcc
	v_mov_b32_e32 v31, 0x5f00000
; #define LAS __attribute__((address_space(3)))
; #define GAS __attribute__((address_space(1)))
; __device__ __forceinline__ void p0_transpose_item(const GAS float* W, int K, int N, GAS bf16* WT, int mode, LAS float* scr, int item, int lane) {
;     const int nblk = N / 32, kb = item / nblk, nb = item % nblk, k0 = 64 * kb, n0 = 32 * nb;
;     int r0 = n0;
;     if (mode & 1) { r0 = (n0 < DFF) ? (n0 / 128) * 256 + (n0 % 128) : ((n0 - DFF) / 128) * 256 + 128 + ((n0 - DFF) % 128); }
; __device__ __forceinline__ void p0_prologue(ArgP A, LAS unsigned char* lds, int tid, int lane, int wave, int bid, int G) {
;     ...
;     constexpr int I_IN = 32 * 165, I_OUT = 32 * 64, I_GU = 32 * 352, I_DN = 88 * 64, I_GT = 32 * 64, I_PL = 4 * 64, I_L = I_IN + I_OUT + I_GU + I_DN + I_GT + I_PL;
;     for (int it = gw; it < 2 * I_L; it += NGW) {
;         const int layer = it / I_L; int r = it - layer * I_L;
;         GAS unsigned char* wb = A->ws + (size_t)layer * WL_BYTES;
;         if (r < I_IN) { p0_transpose_item(A->in[12] + (size_t)layer * DM * 5280, DM, 5280, (GAS bf16*)(wb + WO_IN), 0 | (layer ? 2 : 0), scr, r, lane); continue; } r -= I_IN;
;         if (r < I_OUT) { p0_transpose_item(A->in[33] + (size_t)layer * DM * DM, DM, DM, (GAS bf16*)(wb + WO_OUT), 0 | (layer ? 2 : 0), scr, r, lane); continue; } r -= I_OUT;
;         if (r < I_GU) { p0_transpose_item(A->in[34] + (size_t)layer * DM * 2 * DFF, DM, 2 * DFF, (GAS bf16*)(wb + WO_GU), 1 | (layer ? 2 : 0), scr, r, lane); continue; } r -= I_GU;
;         if (r < I_DN) { p0_transpose_item(A->in[35] + (size_t)layer * DFF * DM, DFF, DM, (GAS bf16*)(wb + WO_DN), 0 | (layer ? 2 : 0), scr, r, lane); continue; } r -= I_DN;
;         if (r < I_GT) { p0_transpose_item(A->in[36] + (size_t)layer * DM * DM, DM, DM, (GAS bf16*)(wb + WO_GT), 0 | (layer ? 2 : 0), scr, r, lane); continue; } r -= I_GT;
;         p0_transpose_item(A->in[37] + (size_t)layer * PLED * DM, PLED, DM, (GAS bf16*)(wb + WO_PL), 0 | (layer ? 2 : 0), scr, r, lane);
	v_cndmask_b32_e32 v7, v7, v31, vcc
	v_mov_b32_e32 v31, s62
	v_cndmask_b32_e32 v96, v96, v31, vcc
	v_mov_b32_e32 v31, s63
	v_cndmask_b32_e32 v97, v97, v31, vcc
	s_movk_i32 s24, 0x66a0
	v_cmp_le_u32_e32 vcc, s24, v4
	v_mov_b32_e32 v31, 0x66a0
	v_cndmask_b32_e32 v5, v5, v31, vcc
	v_mov_b32_e32 v31, 0x800
	v_cndmask_b32_e32 v100, v100, v31, vcc
	v_mov_b32_e32 v31, 0x100
	v_cndmask_b32_e32 v101, v101, v31, vcc
	v_mov_b32_e32 v31, 0x200000
	v_cndmask_b32_e32 v6, v6, v31, vcc
	v_mov_b32_e32 v31, 0x6700000
	v_cndmask_b32_e32 v7, v7, v31, vcc
	v_mov_b32_e32 v31, s18
	v_cndmask_b32_e32 v96, v96, v31, vcc
	v_mov_b32_e32 v31, s19
	v_cndmask_b32_e32 v97, v97, v31, vcc
	v_sub_u32_e32 v4, v4, v5
	v_lshrrev_b32_e32 v5, 6, v4
	v_mov_b32_e32 v8, 64
	s_movk_i32 s24, 0x14a0
	v_cmp_eq_u32_e32 vcc, s24, v100
	v_mul_u32_u24_e32 v31, 0x635, v4
	v_lshrrev_b32_e32 v31, 18, v31
	v_cndmask_b32_e32 v5, v5, v31, vcc
	v_mov_b32_e32 v31, 0xa5
	v_cndmask_b32_e32 v8, v8, v31, vcc
	s_movk_i32 s24, 0x2c00
	v_cmp_eq_u32_e32 vcc, s24, v100
	v_mul_u32_u24_e32 v31, 0xba3, v4
	v_lshrrev_b32_e32 v31, 20, v31
	v_cndmask_b32_e32 v5, v5, v31, vcc
	v_mov_b32_e32 v31, 0x160
	v_cndmask_b32_e32 v8, v8, v31, vcc
	v_mul_u32_u24_e32 v8, v5, v8
	v_sub_u32_e32 v4, v4, v8
	v_lshlrev_b32_e32 v4, 5, v4
	s_movk_i32 s24, 0x1600
	v_cmp_le_u32_e64 s[8:9], s24, v4
	v_subrev_u32_e32 v8, s24, v4
	v_cndmask_b32_e64 v8, v4, v8, s[8:9]
	v_cndmask_b32_e64 v31, 0, 1, s[8:9]
	v_lshlrev_b32_e32 v31, 7, v31
	v_and_b32_e32 v1, 0x7f, v8
	v_lshrrev_b32_e32 v8, 7, v8
	v_lshl_add_u32 v8, v8, 8, v1
	v_add_u32_e32 v8, v8, v31
	v_cndmask_b32_e32 v8, v4, v8, vcc
	v_lshlrev_b32_e32 v1, 5, v2
	v_lshl_add_u32 v1, v5, 6, v1
	v_mul_lo_u32 v1, v1, v100
	v_add_u32_e32 v1, v1, v4
	v_lshlrev_b32_e32 v1, 2, v1
	v_mul_lo_u32 v6, v6, v3
	v_add_u32_e32 v1, v1, v6
	v_add_co_u32_e32 v96, vcc, v96, v1
	v_addc_co_u32_e32 v97, vcc, 0, v97, vcc
	v_lshlrev_b32_e32 v101, 1, v101
	v_mul_lo_u32 v8, v8, v101
	v_add_u32_e32 v8, v8, v7
	v_lshl_add_u32 v8, v5, 7, v8
	v_lshl_add_u32 v8, v2, 6, v8
	s_mov_b32 s24, 0x6800000
	v_mul_lo_u32 v1, v3, s24
	v_add_u32_e32 v8, v8, v1
	v_mov_b32_e32 v1, s7
	v_add_co_u32_e32 v98, vcc, s6, v8
	v_addc_co_u32_e32 v99, vcc, 0, v1, vcc
	v_add_u32_e32 v1, 64, v22
	v_lshl_add_u32 v1, v1, 9, s2
	v_and_b32_e32 v2, 1, v1
	v_lshrrev_b32_e32 v1, 1, v1
	s_movk_i32 s24, 0x67a0
	v_cmp_le_u32_e32 vcc, s24, v1
	v_cndmask_b32_e64 v3, 0, 1, vcc
	v_mul_u32_u24_e32 v4, 0x67a0, v3
	v_sub_u32_e32 v4, v1, v4
	v_mov_b32_e32 v5, 0
	v_mov_b32_e32 v106, 0x14a0
	v_mov_b32_e32 v107, 0x800
	v_mov_b32_e32 v6, 0x2940000
	v_mov_b32_e32 v7, 0x0
	v_mov_b32_e32 v102, s28
	v_mov_b32_e32 v103, s29
	s_movk_i32 s24, 0x14a0
	v_cmp_le_u32_e32 vcc, s24, v4
	v_mov_b32_e32 v31, 0x14a0
	v_cndmask_b32_e32 v5, v5, v31, vcc
	v_mov_b32_e32 v31, 0x800
	v_cndmask_b32_e32 v106, v106, v31, vcc
	v_mov_b32_e32 v31, 0x800
	v_cndmask_b32_e32 v107, v107, v31, vcc
	v_mov_b32_e32 v31, 0x1000000
	v_cndmask_b32_e32 v6, v6, v31, vcc
	v_mov_b32_e32 v31, 0x1500000
	v_cndmask_b32_e32 v7, v7, v31, vcc
	v_mov_b32_e32 v31, s30
	v_cndmask_b32_e32 v102, v102, v31, vcc
	v_mov_b32_e32 v31, s31
	v_cndmask_b32_e32 v103, v103, v31, vcc
	s_movk_i32 s24, 0x1ca0
	v_cmp_le_u32_e32 vcc, s24, v4
	v_mov_b32_e32 v31, 0x1ca0
	v_cndmask_b32_e32 v5, v5, v31, vcc
	v_mov_b32_e32 v31, 0x2c00
	v_cndmask_b32_e32 v106, v106, v31, vcc
	v_mov_b32_e32 v31, 0x800
	v_cndmask_b32_e32 v107, v107, v31, vcc
	v_mov_b32_e32 v31, 0x5800000
	v_cndmask_b32_e32 v6, v6, v31, vcc
	v_mov_b32_e32 v31, 0x1d00000
	v_cndmask_b32_e32 v7, v7, v31, vcc
	v_mov_b32_e32 v31, s32
	v_cndmask_b32_e32 v102, v102, v31, vcc
	v_mov_b32_e32 v31, s33
	v_cndmask_b32_e32 v103, v103, v31, vcc
	s_movk_i32 s24, 0x48a0
	v_cmp_le_u32_e32 vcc, s24, v4
	v_mov_b32_e32 v31, 0x48a0
	v_cndmask_b32_e32 v5, v5, v31, vcc
	v_mov_b32_e32 v31, 0x800
	v_cndmask_b32_e32 v106, v106, v31, vcc
	v_mov_b32_e32 v31, 0x1600
	v_cndmask_b32_e32 v107, v107, v31, vcc
	v_mov_b32_e32 v31, 0x2c00000
	v_cndmask_b32_e32 v6, v6, v31, vcc
	v_mov_b32_e32 v31, 0x4900000
	v_cndmask_b32_e32 v7, v7, v31, vcc
	v_mov_b32_e32 v31, s44
	v_cndmask_b32_e32 v102, v102, v31, vcc
	v_mov_b32_e32 v31, s45
	v_cndmask_b32_e32 v103, v103, v31, vcc
	s_movk_i32 s24, 0x5ea0
	v_cmp_le_u32_e32 vcc, s24, v4
	v_mov_b32_e32 v31, 0x5ea0
	v_cndmask_b32_e32 v5, v5, v31, vcc
	v_mov_b32_e32 v31, 0x800
	v_cndmask_b32_e32 v106, v106, v31, vcc
	v_mov_b32_e32 v31, 0x800
	v_cndmask_b32_e32 v107, v107, v31, vcc
	v_mov_b32_e32 v31, 0x1000000
	v_cndmask_b32_e32 v6, v6, v31, vcc
	v_mov_b32_e32 v31, 0x5f00000
	v_cndmask_b32_e32 v7, v7, v31, vcc
	v_mov_b32_e32 v31, s62
	v_cndmask_b32_e32 v102, v102, v31, vcc
	v_mov_b32_e32 v31, s63
	v_cndmask_b32_e32 v103, v103, v31, vcc
	s_movk_i32 s24, 0x66a0
	v_cmp_le_u32_e32 vcc, s24, v4
	v_mov_b32_e32 v31, 0x66a0
	v_cndmask_b32_e32 v5, v5, v31, vcc
	v_mov_b32_e32 v31, 0x800
	v_cndmask_b32_e32 v106, v106, v31, vcc
	v_mov_b32_e32 v31, 0x100
	v_cndmask_b32_e32 v107, v107, v31, vcc
	v_mov_b32_e32 v31, 0x200000
	v_cndmask_b32_e32 v6, v6, v31, vcc
	v_mov_b32_e32 v31, 0x6700000
	v_cndmask_b32_e32 v7, v7, v31, vcc
	v_mov_b32_e32 v31, s18
	v_cndmask_b32_e32 v102, v102, v31, vcc
	v_mov_b32_e32 v31, s19
	v_cndmask_b32_e32 v103, v103, v31, vcc
	v_sub_u32_e32 v4, v4, v5
	v_lshrrev_b32_e32 v5, 6, v4
	v_mov_b32_e32 v8, 64
	s_movk_i32 s24, 0x14a0
	v_cmp_eq_u32_e32 vcc, s24, v106
	v_mul_u32_u24_e32 v31, 0x635, v4
	v_lshrrev_b32_e32 v31, 18, v31
	v_cndmask_b32_e32 v5, v5, v31, vcc
	v_mov_b32_e32 v31, 0xa5
	v_cndmask_b32_e32 v8, v8, v31, vcc
	s_movk_i32 s24, 0x2c00
	v_cmp_eq_u32_e32 vcc, s24, v106
	v_mul_u32_u24_e32 v31, 0xba3, v4
	v_lshrrev_b32_e32 v31, 20, v31
	v_cndmask_b32_e32 v5, v5, v31, vcc
	v_mov_b32_e32 v31, 0x160
	v_cndmask_b32_e32 v8, v8, v31, vcc
	v_mul_u32_u24_e32 v8, v5, v8
	v_sub_u32_e32 v4, v4, v8
	v_lshlrev_b32_e32 v4, 5, v4
	s_movk_i32 s24, 0x1600
	v_cmp_le_u32_e64 s[8:9], s24, v4
	v_subrev_u32_e32 v8, s24, v4
	v_cndmask_b32_e64 v8, v4, v8, s[8:9]
	v_cndmask_b32_e64 v31, 0, 1, s[8:9]
	v_lshlrev_b32_e32 v31, 7, v31
	v_and_b32_e32 v1, 0x7f, v8
	v_lshrrev_b32_e32 v8, 7, v8
	v_lshl_add_u32 v8, v8, 8, v1
	v_add_u32_e32 v8, v8, v31
	v_cndmask_b32_e32 v8, v4, v8, vcc
	v_lshlrev_b32_e32 v1, 5, v2
	v_lshl_add_u32 v1, v5, 6, v1
	v_mul_lo_u32 v1, v1, v106
	v_add_u32_e32 v1, v1, v4
	v_lshlrev_b32_e32 v1, 2, v1
	v_mul_lo_u32 v6, v6, v3
	v_add_u32_e32 v1, v1, v6
	v_add_co_u32_e32 v102, vcc, v102, v1
	v_addc_co_u32_e32 v103, vcc, 0, v103, vcc
	v_lshlrev_b32_e32 v107, 1, v107
	v_mul_lo_u32 v8, v8, v107
	v_add_u32_e32 v8, v8, v7
	v_lshl_add_u32 v8, v5, 7, v8
	v_lshl_add_u32 v8, v2, 6, v8
	s_mov_b32 s24, 0x6800000
	v_mul_lo_u32 v1, v3, s24
	v_add_u32_e32 v8, v8, v1
	v_mov_b32_e32 v1, s7
	v_add_co_u32_e32 v104, vcc, s6, v8
	v_addc_co_u32_e32 v105, vcc, 0, v1, vcc
	s_mov_b32 s23, 0
	s_mov_b32 s22, 0
	s_mov_b32 s14, 0
	s_mov_b32 s17, 0
	s_mov_b32 s18, 0

; #define LAS __attribute__((address_space(3)))
; #define R4_ISSUE(cc, slot) do { const GAS float* g_ = gp + (size_t)(cc) * 2048; LAS float* l_ = ring + (slot) * 1536; _Pragma("unroll") for (int i_ = 0; i_ < 6; ++i_) \
;         __builtin_amdgcn_global_load_lds((const GAS unsigned*)(g_ + off[i_]), (LAS unsigned*)(l_ + i_ * 256), 16, 0, 0); } while (0)
; #define R4_LOAD(o, sb_) do { const LAS float* sb = (sb_); (o).r = *(const LAS f32x4*)(sb + cgp * 4); (o).w = *(const LAS f32x4*)(sb + 64 + cgp * 4); (o).k = *(const LAS f32x4*)(sb + 128 + cgp * 4); \
;         (o).a = *(const LAS f32x4*)(sb + 256 + cgp * 4); (o).b = *(const LAS f32x4*)(sb + 320 + cgp * 4); (o).vv = sb[192 + rq * 4 + rl]; asm volatile("" ::: "memory"); } while (0)
; __device__ __forceinline__ void rwkv_prompt_wave4(LAS float* ring, const GAS float* RW, int mbase, int h, int rq, GAS float* Sout, GAS float* YR, int lane) {
;     ...
;     for (int cc = 0; cc < 3; ++cc) R4_ISSUE(cc, cc);
;     float ykeep = 0.f;
;     R4Ops oA, oB, oC, oD;
;     asm volatile("s_waitcnt vmcnt(12)" ::: "memory");
;     R4_LOAD(oA, ring); R4_LOAD(oB, ring + 384);
;     for (int ci = 0; ci < NCH; ++ci) {
;         { const int cn = ci + 3; const int cl = cn < NCH ? cn : NCH - 1; R4_ISSUE(cl, cn % R4_NS); }
;         const LAS float* cb = ring + (ci % R4_NS) * 1536; const LAS float* nb = ring + ((ci + 1) % R4_NS) * 1536;
;         R4_LOAD(oC, cb + 768);  R4_STEP(oA, 0);
;         R4_LOAD(oD, cb + 1152); R4_STEP(oB, 1);
;         asm volatile("s_waitcnt vmcnt(12)" ::: "memory");
.Lld_loop:
	s_cmp_eq_u32 s18, 0x80
	s_cbranch_scc1 .Lld_bar
	s_cmp_ge_u32 s1, 2
	s_cbranch_scc1 .Lld_w1
	s_cmp_eq_u32 s18, 0
	s_cbranch_scc1 .Lld_w0a
	s_cmp_eq_u32 s18, 1
	s_cbranch_scc1 .Lld_w0b
	s_cmp_eq_u32 s18, 2
	s_cbranch_scc1 .Lld_w0c
	s_waitcnt vmcnt(30)
	s_branch .Lld_bar

; #define LAS __attribute__((address_space(3)))
; #define R4_ISSUE(cc, slot) do { const GAS float* g_ = gp + (size_t)(cc) * 2048; LAS float* l_ = ring + (slot) * 1536; _Pragma("unroll") for (int i_ = 0; i_ < 6; ++i_) \
;         __builtin_amdgcn_global_load_lds((const GAS unsigned*)(g_ + off[i_]), (LAS unsigned*)(l_ + i_ * 256), 16, 0, 0); } while (0)
; #define R4_LOAD(o, sb_) do { const LAS float* sb = (sb_); (o).r = *(const LAS f32x4*)(sb + cgp * 4); (o).w = *(const LAS f32x4*)(sb + 64 + cgp * 4); (o).k = *(const LAS f32x4*)(sb + 128 + cgp * 4); \
;         (o).a = *(const LAS f32x4*)(sb + 256 + cgp * 4); (o).b = *(const LAS f32x4*)(sb + 320 + cgp * 4); (o).vv = sb[192 + rq * 4 + rl]; asm volatile("" ::: "memory"); } while (0)
; __device__ __forceinline__ void rwkv_prompt_wave4(LAS float* ring, const GAS float* RW, int mbase, int h, int rq, GAS float* Sout, GAS float* YR, int lane) {
;     ...
;     for (int cc = 0; cc < 3; ++cc) R4_ISSUE(cc, cc);
;     float ykeep = 0.f;
;     R4Ops oA, oB, oC, oD;
;     asm volatile("s_waitcnt vmcnt(12)" ::: "memory");
;     R4_LOAD(oA, ring); R4_LOAD(oB, ring + 384);
;     for (int ci = 0; ci < NCH; ++ci) {
;         { const int cn = ci + 3; const int cl = cn < NCH ? cn : NCH - 1; R4_ISSUE(cl, cn % R4_NS); }
;         const LAS float* cb = ring + (ci % R4_NS) * 1536; const LAS float* nb = ring + ((ci + 1) % R4_NS) * 1536;
;         R4_LOAD(oC, cb + 768);  R4_STEP(oA, 0);
;         R4_LOAD(oD, cb + 1152); R4_STEP(oB, 1);
;         asm volatile("s_waitcnt vmcnt(12)" ::: "memory");
.Lld_w0c:
	s_waitcnt vmcnt(26)
	s_branch .Lld_bar
.Lld_w1:
	s_cmp_eq_u32 s18, 0
	s_cbranch_scc1 .Lld_w1a
	s_cmp_eq_u32 s18, 1
	s_cbranch_scc1 .Lld_w1b
	s_cmp_eq_u32 s18, 2
	s_cbranch_scc1 .Lld_w1c
	s_waitcnt vmcnt(23)
	s_branch .Lld_bar

; #define LAS __attribute__((address_space(3)))
; #define R4_ISSUE(cc, slot) do { const GAS float* g_ = gp + (size_t)(cc) * 2048; LAS float* l_ = ring + (slot) * 1536; _Pragma("unroll") for (int i_ = 0; i_ < 6; ++i_) \
;         __builtin_amdgcn_global_load_lds((const GAS unsigned*)(g_ + off[i_]), (LAS unsigned*)(l_ + i_ * 256), 16, 0, 0); } while (0)
; #define R4_LOAD(o, sb_) do { const LAS float* sb = (sb_); (o).r = *(const LAS f32x4*)(sb + cgp * 4); (o).w = *(const LAS f32x4*)(sb + 64 + cgp * 4); (o).k = *(const LAS f32x4*)(sb + 128 + cgp * 4); \
;         (o).a = *(const LAS f32x4*)(sb + 256 + cgp * 4); (o).b = *(const LAS f32x4*)(sb + 320 + cgp * 4); (o).vv = sb[192 + rq * 4 + rl]; asm volatile("" ::: "memory"); } while (0)
; __device__ __forceinline__ void rwkv_prompt_wave4(LAS float* ring, const GAS float* RW, int mbase, int h, int rq, GAS float* Sout, GAS float* YR, int lane) {
;     ...
;     for (int cc = 0; cc < 3; ++cc) R4_ISSUE(cc, cc);
;     float ykeep = 0.f;
;     R4Ops oA, oB, oC, oD;
;     asm volatile("s_waitcnt vmcnt(12)" ::: "memory");
;     R4_LOAD(oA, ring); R4_LOAD(oB, ring + 384);
;     for (int ci = 0; ci < NCH; ++ci) {
;         { const int cn = ci + 3; const int cl = cn < NCH ? cn : NCH - 1; R4_ISSUE(cl, cn % R4_NS); }
;         const LAS float* cb = ring + (ci % R4_NS) * 1536; const LAS float* nb = ring + ((ci + 1) % R4_NS) * 1536;
;         R4_LOAD(oC, cb + 768);  R4_STEP(oA, 0);
;         R4_LOAD(oD, cb + 1152); R4_STEP(oB, 1);
;         asm volatile("s_waitcnt vmcnt(12)" ::: "memory");
.Lld_w1b:
	s_waitcnt vmcnt(11)
	s_branch .Lld_bar
.Lld_w1c:
	s_waitcnt vmcnt(19)

; __device__ __forceinline__ void rwkv_prompt_wave4(LAS float* ring, const GAS float* RW, int mbase, int h, int rq, GAS float* Sout, GAS float* YR, int lane) {
;     ...
;         if (cgp < 4) YR[(size_t)(mbase + ci * 4 + cgp) * 512 + h * 64 + rq * 4 + rl] = ykeep;
.Lld_y:
	v_add_u32_e32 v28, s22, v25
	ds_read_b32 v32, v28
	ds_read_b32 v33, v28 offset:256
	ds_read_b32 v34, v28 offset:512
	ds_read_b32 v35, v28 offset:768
	s_add_i32 s22, s22, 0x400
	s_and_b32 s22, s22, 0x1fff
	v_add_u32_e32 v28, s22, v25
	ds_read_b32 v36, v28
	ds_read_b32 v37, v28 offset:256
	ds_read_b32 v38, v28 offset:512
	ds_read_b32 v39, v28 offset:768
	s_add_i32 s22, s22, 0x400
	s_and_b32 s22, s22, 0x1fff
	v_add_u32_e32 v28, s22, v25
	ds_read_b32 v40, v28
	ds_read_b32 v41, v28 offset:256
	ds_read_b32 v42, v28 offset:512
	ds_read_b32 v43, v28 offset:768
	s_add_i32 s22, s22, 0x400
	s_and_b32 s22, s22, 0x1fff
	v_add_u32_e32 v28, s22, v25
	ds_read_b32 v44, v28
	ds_read_b32 v45, v28 offset:256
	ds_read_b32 v46, v28 offset:512
	ds_read_b32 v47, v28 offset:768
	s_add_i32 s22, s22, 0x400
	s_and_b32 s22, s22, 0x1fff
	s_waitcnt lgkmcnt(12)
	v_add_f32_dpp v32, v32, v32 quad_perm:[1,0,3,2] row_mask:0xf bank_mask:0xf bound_ctrl:1
	v_add_f32_dpp v33, v33, v33 quad_perm:[1,0,3,2] row_mask:0xf bank_mask:0xf bound_ctrl:1
	v_add_f32_dpp v34, v34, v34 quad_perm:[1,0,3,2] row_mask:0xf bank_mask:0xf bound_ctrl:1
	v_add_f32_dpp v35, v35, v35 quad_perm:[1,0,3,2] row_mask:0xf bank_mask:0xf bound_ctrl:1
	v_add_f32_dpp v32, v32, v32 quad_perm:[2,3,0,1] row_mask:0xf bank_mask:0xf bound_ctrl:1
	v_add_f32_dpp v33, v33, v33 quad_perm:[2,3,0,1] row_mask:0xf bank_mask:0xf bound_ctrl:1
	v_add_f32_dpp v34, v34, v34 quad_perm:[2,3,0,1] row_mask:0xf bank_mask:0xf bound_ctrl:1
	v_add_f32_dpp v35, v35, v35 quad_perm:[2,3,0,1] row_mask:0xf bank_mask:0xf bound_ctrl:1
	v_add_f32_dpp v32, v32, v32 row_half_mirror row_mask:0xf bank_mask:0xf bound_ctrl:1
	v_add_f32_dpp v33, v33, v33 row_half_mirror row_mask:0xf bank_mask:0xf bound_ctrl:1
	v_add_f32_dpp v34, v34, v34 row_half_mirror row_mask:0xf bank_mask:0xf bound_ctrl:1
	v_add_f32_dpp v35, v35, v35 row_half_mirror row_mask:0xf bank_mask:0xf bound_ctrl:1
	v_add_f32_dpp v32, v32, v32 row_mirror row_mask:0xf bank_mask:0xf bound_ctrl:1
	v_add_f32_dpp v33, v33, v33 row_mirror row_mask:0xf bank_mask:0xf bound_ctrl:1
	v_add_f32_dpp v34, v34, v34 row_mirror row_mask:0xf bank_mask:0xf bound_ctrl:1
	v_add_f32_dpp v35, v35, v35 row_mirror row_mask:0xf bank_mask:0xf bound_ctrl:1
	v_cmp_eq_u32_e32 vcc, 0, v23
	v_cndmask_b32_e32 v33, v33, v32, vcc
	v_cmp_eq_u32_e32 vcc, 2, v23
	v_cndmask_b32_e32 v33, v33, v34, vcc
	v_cmp_eq_u32_e32 vcc, 3, v23
	v_cndmask_b32_e32 v33, v33, v35, vcc
	v_cmp_gt_u32_e32 vcc, 4, v23
	s_nop 1
	s_mov_b64 exec, vcc
	global_store_dword v27, v33, s[98:99]
	s_mov_b64 exec, -1
	s_add_u32 s98, s98, 0x2000
	s_addc_u32 s99, s99, 0
	s_nop 2
	s_waitcnt lgkmcnt(8)
	v_add_f32_dpp v36, v36, v36 quad_perm:[1,0,3,2] row_mask:0xf bank_mask:0xf bound_ctrl:1
	v_add_f32_dpp v37, v37, v37 quad_perm:[1,0,3,2] row_mask:0xf bank_mask:0xf bound_ctrl:1
	v_add_f32_dpp v38, v38, v38 quad_perm:[1,0,3,2] row_mask:0xf bank_mask:0xf bound_ctrl:1
	v_add_f32_dpp v39, v39, v39 quad_perm:[1,0,3,2] row_mask:0xf bank_mask:0xf bound_ctrl:1
	v_add_f32_dpp v36, v36, v36 quad_perm:[2,3,0,1] row_mask:0xf bank_mask:0xf bound_ctrl:1
	v_add_f32_dpp v37, v37, v37 quad_perm:[2,3,0,1] row_mask:0xf bank_mask:0xf bound_ctrl:1
	v_add_f32_dpp v38, v38, v38 quad_perm:[2,3,0,1] row_mask:0xf bank_mask:0xf bound_ctrl:1
	v_add_f32_dpp v39, v39, v39 quad_perm:[2,3,0,1] row_mask:0xf bank_mask:0xf bound_ctrl:1
	v_add_f32_dpp v36, v36, v36 row_half_mirror row_mask:0xf bank_mask:0xf bound_ctrl:1
	v_add_f32_dpp v37, v37, v37 row_half_mirror row_mask:0xf bank_mask:0xf bound_ctrl:1
	v_add_f32_dpp v38, v38, v38 row_half_mirror row_mask:0xf bank_mask:0xf bound_ctrl:1
	v_add_f32_dpp v39, v39, v39 row_half_mirror row_mask:0xf bank_mask:0xf bound_ctrl:1
	v_add_f32_dpp v36, v36, v36 row_mirror row_mask:0xf bank_mask:0xf bound_ctrl:1
	v_add_f32_dpp v37, v37, v37 row_mirror row_mask:0xf bank_mask:0xf bound_ctrl:1
	v_add_f32_dpp v38, v38, v38 row_mirror row_mask:0xf bank_mask:0xf bound_ctrl:1
	v_add_f32_dpp v39, v39, v39 row_mirror row_mask:0xf bank_mask:0xf bound_ctrl:1
	v_cmp_eq_u32_e32 vcc, 0, v23
	v_cndmask_b32_e32 v37, v37, v36, vcc
	v_cmp_eq_u32_e32 vcc, 2, v23
	v_cndmask_b32_e32 v37, v37, v38, vcc
	v_cmp_eq_u32_e32 vcc, 3, v23
	v_cndmask_b32_e32 v37, v37, v39, vcc
	v_cmp_gt_u32_e32 vcc, 4, v23
	s_nop 1
	s_mov_b64 exec, vcc
	global_store_dword v27, v37, s[98:99]
	s_mov_b64 exec, -1
	s_add_u32 s98, s98, 0x2000
	s_addc_u32 s99, s99, 0
	s_nop 2
	s_waitcnt lgkmcnt(4)
	v_add_f32_dpp v40, v40, v40 quad_perm:[1,0,3,2] row_mask:0xf bank_mask:0xf bound_ctrl:1
	v_add_f32_dpp v41, v41, v41 quad_perm:[1,0,3,2] row_mask:0xf bank_mask:0xf bound_ctrl:1
	v_add_f32_dpp v42, v42, v42 quad_perm:[1,0,3,2] row_mask:0xf bank_mask:0xf bound_ctrl:1
	v_add_f32_dpp v43, v43, v43 quad_perm:[1,0,3,2] row_mask:0xf bank_mask:0xf bound_ctrl:1
	v_add_f32_dpp v40, v40, v40 quad_perm:[2,3,0,1] row_mask:0xf bank_mask:0xf bound_ctrl:1
	v_add_f32_dpp v41, v41, v41 quad_perm:[2,3,0,1] row_mask:0xf bank_mask:0xf bound_ctrl:1
	v_add_f32_dpp v42, v42, v42 quad_perm:[2,3,0,1] row_mask:0xf bank_mask:0xf bound_ctrl:1
	v_add_f32_dpp v43, v43, v43 quad_perm:[2,3,0,1] row_mask:0xf bank_mask:0xf bound_ctrl:1
	v_add_f32_dpp v40, v40, v40 row_half_mirror row_mask:0xf bank_mask:0xf bound_ctrl:1
	v_add_f32_dpp v41, v41, v41 row_half_mirror row_mask:0xf bank_mask:0xf bound_ctrl:1
	v_add_f32_dpp v42, v42, v42 row_half_mirror row_mask:0xf bank_mask:0xf bound_ctrl:1
	v_add_f32_dpp v43, v43, v43 row_half_mirror row_mask:0xf bank_mask:0xf bound_ctrl:1
	v_add_f32_dpp v40, v40, v40 row_mirror row_mask:0xf bank_mask:0xf bound_ctrl:1
	v_add_f32_dpp v41, v41, v41 row_mirror row_mask:0xf bank_mask:0xf bound_ctrl:1
	v_add_f32_dpp v42, v42, v42 row_mirror row_mask:0xf bank_mask:0xf bound_ctrl:1
	v_add_f32_dpp v43, v43, v43 row_mirror row_mask:0xf bank_mask:0xf bound_ctrl:1
	v_cmp_eq_u32_e32 vcc, 0, v23
	v_cndmask_b32_e32 v41, v41, v40, vcc
	v_cmp_eq_u32_e32 vcc, 2, v23
	v_cndmask_b32_e32 v41, v41, v42, vcc
	v_cmp_eq_u32_e32 vcc, 3, v23
	v_cndmask_b32_e32 v41, v41, v43, vcc
	v_cmp_gt_u32_e32 vcc, 4, v23
	s_nop 1
	s_mov_b64 exec, vcc
	global_store_dword v27, v41, s[98:99]
	s_mov_b64 exec, -1
	s_add_u32 s98, s98, 0x2000
	s_addc_u32 s99, s99, 0
	s_nop 2
	s_waitcnt lgkmcnt(0)
; #define LAS __attribute__((address_space(3)))
; #define GAS __attribute__((address_space(1)))
; __device__ __forceinline__ unsigned pk2(float lo, float hi) { return pg8::cvt_pk_bf16(lo, hi); }
; #define LDS_WAIT() asm volatile("s_waitcnt lgkmcnt(0)" ::: "memory")
; __device__ __forceinline__ void p0_transpose_item(const GAS float* W, int K, int N, GAS bf16* WT, int mode, LAS float* scr, int item, int lane) {
;     ...
;     float tv[32];
; #pragma unroll
;     for (int i = 0; i < 32; ++i) tv[i] = __builtin_nontemporal_load(&W[(size_t)(k0 + 2 * i + (lane >> 5)) * N + n0 + (lane & 31)]);
; #pragma unroll
;     for (int i = 0; i < 32; ++i) scr[(2 * i + (lane >> 5)) * 33 + (lane & 31)] = tv[i];
;     LDS_WAIT();
;     const int c = lane & 7;
; #pragma unroll
;     for (int j = 0; j < 4; ++j) { const int n = (lane >> 3) + 8 * j; const LAS float* s = scr + (8 * c) * 33 + n;
;         u32x4 o; o.x = pk2(s[0 * 33], s[1 * 33]); o.y = pk2(s[2 * 33], s[3 * 33]); o.z = pk2(s[4 * 33], s[5 * 33]); o.w = pk2(s[6 * 33], s[7 * 33]);
;         if (mode & 2) __builtin_nontemporal_store(o, (GAS u32x4*)(WT + (size_t)(r0 + n) * K + k0 + 8 * c)); else *(GAS u32x4*)(WT + (size_t)(r0 + n) * K + k0 + 8 * c) = o; }
;     LDS_WAIT();
; }
	v_add_f32_dpp v44, v44, v44 quad_perm:[1,0,3,2] row_mask:0xf bank_mask:0xf bound_ctrl:1
	v_add_f32_dpp v45, v45, v45 quad_perm:[1,0,3,2] row_mask:0xf bank_mask:0xf bound_ctrl:1
	v_add_f32_dpp v46, v46, v46 quad_perm:[1,0,3,2] row_mask:0xf bank_mask:0xf bound_ctrl:1
	v_add_f32_dpp v47, v47, v47 quad_perm:[1,0,3,2] row_mask:0xf bank_mask:0xf bound_ctrl:1
	v_add_f32_dpp v44, v44, v44 quad_perm:[2,3,0,1] row_mask:0xf bank_mask:0xf bound_ctrl:1
	v_add_f32_dpp v45, v45, v45 quad_perm:[2,3,0,1] row_mask:0xf bank_mask:0xf bound_ctrl:1
	v_add_f32_dpp v46, v46, v46 quad_perm:[2,3,0,1] row_mask:0xf bank_mask:0xf bound_ctrl:1
	v_add_f32_dpp v47, v47, v47 quad_perm:[2,3,0,1] row_mask:0xf bank_mask:0xf bound_ctrl:1
	v_add_f32_dpp v44, v44, v44 row_half_mirror row_mask:0xf bank_mask:0xf bound_ctrl:1
	v_add_f32_dpp v45, v45, v45 row_half_mirror row_mask:0xf bank_mask:0xf bound_ctrl:1
	v_add_f32_dpp v46, v46, v46 row_half_mirror row_mask:0xf bank_mask:0xf bound_ctrl:1
	v_add_f32_dpp v47, v47, v47 row_half_mirror row_mask:0xf bank_mask:0xf bound_ctrl:1
	v_add_f32_dpp v44, v44, v44 row_mirror row_mask:0xf bank_mask:0xf bound_ctrl:1
	v_add_f32_dpp v45, v45, v45 row_mirror row_mask:0xf bank_mask:0xf bound_ctrl:1
	v_add_f32_dpp v46, v46, v46 row_mirror row_mask:0xf bank_mask:0xf bound_ctrl:1
	v_add_f32_dpp v47, v47, v47 row_mirror row_mask:0xf bank_mask:0xf bound_ctrl:1
	v_cmp_eq_u32_e32 vcc, 0, v23
	v_cndmask_b32_e32 v45, v45, v44, vcc
	v_cmp_eq_u32_e32 vcc, 2, v23
	v_cndmask_b32_e32 v45, v45, v46, vcc
	v_cmp_eq_u32_e32 vcc, 3, v23
	v_cndmask_b32_e32 v45, v45, v47, vcc
	v_cmp_gt_u32_e32 vcc, 4, v23
	s_nop 1
	s_mov_b64 exec, vcc
	global_store_dword v27, v45, s[98:99]
	s_mov_b64 exec, -1
	s_add_u32 s98, s98, 0x2000
	s_addc_u32 s99, s99, 0
	s_nop 2
.Lld_ynone:
	s_cmp_eq_u32 s18, 0x80
	s_cbranch_scc1 .Lxp_ret
	s_cmp_eq_u32 s23, 0
	s_cbranch_scc1 .Lxp_st0
	s_cmp_eq_u32 s23, 1
	s_cbranch_scc1 .Lxp_st1
	s_branch .Lxp_st2
.Lxp_st0:
	s_sub_u32 s19, s18, 3
	s_cmp_lt_u32 s18, 3
	s_cbranch_scc1 .Lxp_ld0
	s_cmp_ge_u32 s19, s12
	s_cbranch_scc1 .Lxp_ld0
	ds_write_b128 v11, v[48:51] offset:0
	ds_write_b128 v12, v[52:55] offset:1024
	ds_write_b128 v13, v[56:59] offset:2048
	ds_write_b128 v14, v[60:63] offset:3072
.Lxp_ld0:
	s_cmp_ge_u32 s18, s12
	s_cbranch_scc1 .Lxp_dm0
	s_mov_b32 s19, s18
	s_cmp_lt_u32 s18, 64
	s_cbranch_scc1 .Lxp_t1_0
	s_sub_u32 s19, s18, 64
	v_readlane_b32 s62, v102, s19
	v_readlane_b32 s63, v103, s19
	v_readlane_b32 s8, v106, s19
	s_branch .Lxp_go0
.Lxp_t1_0:
	v_readlane_b32 s62, v96, s19
	v_readlane_b32 s63, v97, s19
	v_readlane_b32 s8, v100, s19
.Lxp_go0:
	s_lshl_b32 s9, s8, 2
	v_mad_u32_u24 v7, v9, s9, v15
	s_lshl_b32 s9, s8, 5
	global_load_dwordx4 v[48:51], v7, s[62:63] nt
	v_add_u32_e32 v7, s9, v7
	global_load_dwordx4 v[52:55], v7, s[62:63] nt
	v_add_u32_e32 v7, s9, v7
	global_load_dwordx4 v[56:59], v7, s[62:63] nt
	v_add_u32_e32 v7, s9, v7
	global_load_dwordx4 v[60:63], v7, s[62:63] nt
	s_branch .Lxp_c0
.Lxp_dm0:
	global_load_dword v48, v10, s[4:5]
	global_load_dword v52, v10, s[4:5]
	global_load_dword v56, v10, s[4:5]
	global_load_dword v60, v10, s[4:5]
.Lxp_c0:
	s_sub_u32 s19, s18, 3
	s_cmp_lt_u32 s18, 3
	s_cbranch_scc1 .Lxp_ret
	s_cmp_ge_u32 s19, s12
	s_cbranch_scc1 .Lxp_ret
	s_cmp_lt_u32 s19, 64
	s_cbranch_scc1 .Lxp_u1_0
	s_sub_u32 s19, s19, 64
	v_readlane_b32 s44, v104, s19
	v_readlane_b32 s45, v105, s19
	v_readlane_b32 s30, v107, s19
	s_branch .Lxp_rd0
.Lxp_u1_0:
	v_readlane_b32 s44, v98, s19
	v_readlane_b32 s45, v99, s19
	v_readlane_b32 s30, v101, s19
.Lxp_rd0:
	s_waitcnt lgkmcnt(0)
	ds_read2_b32 v[32:33], v18 offset0:0 offset1:32
	ds_read2_b32 v[34:35], v18 offset0:64 offset1:96
	ds_read2_b32 v[36:37], v18 offset0:128 offset1:160
	ds_read2_b32 v[38:39], v18 offset0:192 offset1:224
	ds_read2_b32 v[40:41], v19 offset0:0 offset1:32
	ds_read2_b32 v[42:43], v19 offset0:64 offset1:96
	ds_read2_b32 v[44:45], v19 offset0:128 offset1:160
	ds_read2_b32 v[46:47], v19 offset0:192 offset1:224
	v_mad_u32_u24 v8, v29, s30, v30
	s_lshl_b32 s31, s30, 4
	s_waitcnt lgkmcnt(4)
	v_cvt_pk_bf16_f32 v32, v32, v33
	v_cvt_pk_bf16_f32 v33, v34, v35
	v_cvt_pk_bf16_f32 v34, v36, v37
	v_cvt_pk_bf16_f32 v35, v38, v39
	global_store_dwordx4 v8, v[32:35], s[44:45]
	v_add_u32_e32 v8, s31, v8
	s_waitcnt lgkmcnt(0)
	v_cvt_pk_bf16_f32 v40, v40, v41
	v_cvt_pk_bf16_f32 v41, v42, v43
	v_cvt_pk_bf16_f32 v42, v44, v45
	v_cvt_pk_bf16_f32 v43, v46, v47
	global_store_dwordx4 v8, v[40:43], s[44:45]
	s_branch .Lxp_ret
.Lxp_st1:
	s_sub_u32 s19, s18, 3
	s_cmp_lt_u32 s18, 3
	s_cbranch_scc1 .Lxp_ld1
	s_cmp_ge_u32 s19, s12
	s_cbranch_scc1 .Lxp_ld1
	ds_write_b128 v11, v[64:67] offset:0
	ds_write_b128 v12, v[68:71] offset:1024
	ds_write_b128 v13, v[72:75] offset:2048
	ds_write_b128 v14, v[76:79] offset:3072

; #define LAS __attribute__((address_space(3)))
; #define GAS __attribute__((address_space(1)))
; __device__ __forceinline__ unsigned pk2(float lo, float hi) { return pg8::cvt_pk_bf16(lo, hi); }
; #define LDS_WAIT() asm volatile("s_waitcnt lgkmcnt(0)" ::: "memory")
; __device__ __forceinline__ void p0_transpose_item(const GAS float* W, int K, int N, GAS bf16* WT, int mode, LAS float* scr, int item, int lane) {
;     ...
;     float tv[32];
; #pragma unroll
;     for (int i = 0; i < 32; ++i) tv[i] = __builtin_nontemporal_load(&W[(size_t)(k0 + 2 * i + (lane >> 5)) * N + n0 + (lane & 31)]);
; #pragma unroll
;     for (int i = 0; i < 32; ++i) scr[(2 * i + (lane >> 5)) * 33 + (lane & 31)] = tv[i];
;     LDS_WAIT();
;     const int c = lane & 7;
; #pragma unroll
;     for (int j = 0; j < 4; ++j) { const int n = (lane >> 3) + 8 * j; const LAS float* s = scr + (8 * c) * 33 + n;
;         u32x4 o; o.x = pk2(s[0 * 33], s[1 * 33]); o.y = pk2(s[2 * 33], s[3 * 33]); o.z = pk2(s[4 * 33], s[5 * 33]); o.w = pk2(s[6 * 33], s[7 * 33]);
;         if (mode & 2) __builtin_nontemporal_store(o, (GAS u32x4*)(WT + (size_t)(r0 + n) * K + k0 + 8 * c)); else *(GAS u32x4*)(WT + (size_t)(r0 + n) * K + k0 + 8 * c) = o; }
.Lxp_go1:
	s_lshl_b32 s9, s8, 2
	v_mad_u32_u24 v7, v9, s9, v15
	s_lshl_b32 s9, s8, 5
	global_load_dwordx4 v[64:67], v7, s[62:63] nt
	v_add_u32_e32 v7, s9, v7
	global_load_dwordx4 v[68:71], v7, s[62:63] nt
	v_add_u32_e32 v7, s9, v7
	global_load_dwordx4 v[72:75], v7, s[62:63] nt
	v_add_u32_e32 v7, s9, v7
	global_load_dwordx4 v[76:79], v7, s[62:63] nt
	s_branch .Lxp_c1
.Lxp_dm1:
	global_load_dword v64, v10, s[4:5]
	global_load_dword v68, v10, s[4:5]
	global_load_dword v72, v10, s[4:5]
	global_load_dword v76, v10, s[4:5]

; #define LAS __attribute__((address_space(3)))
; #define GAS __attribute__((address_space(1)))
; __device__ __forceinline__ unsigned pk2(float lo, float hi) { return pg8::cvt_pk_bf16(lo, hi); }
; #define LDS_WAIT() asm volatile("s_waitcnt lgkmcnt(0)" ::: "memory")
; __device__ __forceinline__ void p0_transpose_item(const GAS float* W, int K, int N, GAS bf16* WT, int mode, LAS float* scr, int item, int lane) {
;     ...
;     float tv[32];
; #pragma unroll
;     for (int i = 0; i < 32; ++i) tv[i] = __builtin_nontemporal_load(&W[(size_t)(k0 + 2 * i + (lane >> 5)) * N + n0 + (lane & 31)]);
; #pragma unroll
;     for (int i = 0; i < 32; ++i) scr[(2 * i + (lane >> 5)) * 33 + (lane & 31)] = tv[i];
;     LDS_WAIT();
;     const int c = lane & 7;
; #pragma unroll
;     for (int j = 0; j < 4; ++j) { const int n = (lane >> 3) + 8 * j; const LAS float* s = scr + (8 * c) * 33 + n;
;         u32x4 o; o.x = pk2(s[0 * 33], s[1 * 33]); o.y = pk2(s[2 * 33], s[3 * 33]); o.z = pk2(s[4 * 33], s[5 * 33]); o.w = pk2(s[6 * 33], s[7 * 33]);
;         if (mode & 2) __builtin_nontemporal_store(o, (GAS u32x4*)(WT + (size_t)(r0 + n) * K + k0 + 8 * c)); else *(GAS u32x4*)(WT + (size_t)(r0 + n) * K + k0 + 8 * c) = o; }
.Lxp_st2:
	s_sub_u32 s19, s18, 3
	s_cmp_lt_u32 s18, 3
	s_cbranch_scc1 .Lxp_ld2
	s_cmp_ge_u32 s19, s12
	s_cbranch_scc1 .Lxp_ld2
	ds_write_b128 v11, v[80:83] offset:0
	ds_write_b128 v12, v[84:87] offset:1024
	ds_write_b128 v13, v[88:91] offset:2048
	ds_write_b128 v14, v[92:95] offset:3072

; #define LAS __attribute__((address_space(3)))
; #define GAS __attribute__((address_space(1)))
; __device__ __forceinline__ unsigned pk2(float lo, float hi) { return pg8::cvt_pk_bf16(lo, hi); }
; #define LDS_WAIT() asm volatile("s_waitcnt lgkmcnt(0)" ::: "memory")
; __device__ __forceinline__ void p0_transpose_item(const GAS float* W, int K, int N, GAS bf16* WT, int mode, LAS float* scr, int item, int lane) {
;     ...
;     float tv[32];
; #pragma unroll
;     for (int i = 0; i < 32; ++i) tv[i] = __builtin_nontemporal_load(&W[(size_t)(k0 + 2 * i + (lane >> 5)) * N + n0 + (lane & 31)]);
; #pragma unroll
;     for (int i = 0; i < 32; ++i) scr[(2 * i + (lane >> 5)) * 33 + (lane & 31)] = tv[i];
;     LDS_WAIT();
;     const int c = lane & 7;
; #pragma unroll
;     for (int j = 0; j < 4; ++j) { const int n = (lane >> 3) + 8 * j; const LAS float* s = scr + (8 * c) * 33 + n;
;         u32x4 o; o.x = pk2(s[0 * 33], s[1 * 33]); o.y = pk2(s[2 * 33], s[3 * 33]); o.z = pk2(s[4 * 33], s[5 * 33]); o.w = pk2(s[6 * 33], s[7 * 33]);
;         if (mode & 2) __builtin_nontemporal_store(o, (GAS u32x4*)(WT + (size_t)(r0 + n) * K + k0 + 8 * c)); else *(GAS u32x4*)(WT + (size_t)(r0 + n) * K + k0 + 8 * c) = o; }
.Lxp_go2:
	s_lshl_b32 s9, s8, 2
	v_mad_u32_u24 v7, v9, s9, v15
	s_lshl_b32 s9, s8, 5
	global_load_dwordx4 v[80:83], v7, s[62:63] nt
	v_add_u32_e32 v7, s9, v7
	global_load_dwordx4 v[84:87], v7, s[62:63] nt
	v_add_u32_e32 v7, s9, v7
	global_load_dwordx4 v[88:91], v7, s[62:63] nt
	v_add_u32_e32 v7, s9, v7
	global_load_dwordx4 v[92:95], v7, s[62:63] nt
	s_branch .Lxp_c2
.Lxp_dm2:
	global_load_dword v80, v10, s[4:5]
	global_load_dword v84, v10, s[4:5]
	global_load_dword v88, v10, s[4:5]
	global_load_dword v92, v10, s[4:5]

; #define LAS __attribute__((address_space(3)))
; #define GAS __attribute__((address_space(1)))
; __device__ __forceinline__ unsigned pk2(float lo, float hi) { return pg8::cvt_pk_bf16(lo, hi); }
; #define LDS_WAIT() asm volatile("s_waitcnt lgkmcnt(0)" ::: "memory")
; __device__ __forceinline__ unsigned xb_add(unsigned* p, unsigned v) { return __hip_atomic_fetch_add(p, v, __ATOMIC_RELAXED, __HIP_MEMORY_SCOPE_AGENT); }
; __device__ __forceinline__ void xcd_barrier(const XcdBarrier& b) {
;     asm volatile("s_waitcnt vmcnt(0)" ::: "memory");
;     __syncthreads();
;     if (threadIdx.x == 0) {
;         unsigned* bar = b.bar;
;         __builtin_amdgcn_s_waitcnt(0);
;         unsigned nloc = b.st[0], nx = b.st[1];
;         if (nloc == 0u) { xcd_barrier_complete(bar, b.x, nloc, nx); b.st[0] = nloc; b.st[1] = nx; }
;         const unsigned old = xb_add(&bar[XB_XSUB(b.x)], 1u);
;         const unsigned gen = old / nloc;
; __device__ __forceinline__ void p0_transpose_item(const GAS float* W, int K, int N, GAS bf16* WT, int mode, LAS float* scr, int item, int lane) {
;     ...
;     float tv[32];
; #pragma unroll
;     for (int i = 0; i < 32; ++i) tv[i] = __builtin_nontemporal_load(&W[(size_t)(k0 + 2 * i + (lane >> 5)) * N + n0 + (lane & 31)]);
; #pragma unroll
;     for (int i = 0; i < 32; ++i) scr[(2 * i + (lane >> 5)) * 33 + (lane & 31)] = tv[i];
;     LDS_WAIT();
;     const int c = lane & 7;
; #pragma unroll
;     for (int j = 0; j < 4; ++j) { const int n = (lane >> 3) + 8 * j; const LAS float* s = scr + (8 * c) * 33 + n;
;         u32x4 o; o.x = pk2(s[0 * 33], s[1 * 33]); o.y = pk2(s[2 * 33], s[3 * 33]); o.z = pk2(s[4 * 33], s[5 * 33]); o.w = pk2(s[6 * 33], s[7 * 33]);
;         if (mode & 2) __builtin_nontemporal_store(o, (GAS u32x4*)(WT + (size_t)(r0 + n) * K + k0 + 8 * c)); else *(GAS u32x4*)(WT + (size_t)(r0 + n) * K + k0 + 8 * c) = o; }
;     LDS_WAIT();
; }
.Lxp_ret:
	s_add_u32 s23, s23, 1
	s_cmp_eq_u32 s23, 3
	s_cselect_b32 s23, 0, s23
	s_add_u32 s18, s18, 1
	s_cmp_le_u32 s18, 0x80
	s_cbranch_scc1 .Lld_loop
	s_waitcnt vmcnt(0)
	s_movk_i32 s19, 125
	s_cmp_ge_u32 s19, s12
	s_cbranch_scc1 .Lxp_dr125
	s_sub_u32 s19, s19, 64
	v_readlane_b32 s44, v104, s19
	v_readlane_b32 s45, v105, s19
	v_readlane_b32 s30, v107, s19
	ds_write_b128 v11, v[80:83] offset:0
	ds_write_b128 v12, v[84:87] offset:1024
	ds_write_b128 v13, v[88:91] offset:2048
	ds_write_b128 v14, v[92:95] offset:3072
	s_waitcnt lgkmcnt(0)
	ds_read2_b32 v[32:33], v18 offset0:0 offset1:32
	ds_read2_b32 v[34:35], v18 offset0:64 offset1:96
	ds_read2_b32 v[36:37], v18 offset0:128 offset1:160
	ds_read2_b32 v[38:39], v18 offset0:192 offset1:224
	ds_read2_b32 v[40:41], v19 offset0:0 offset1:32
	ds_read2_b32 v[42:43], v19 offset0:64 offset1:96
	ds_read2_b32 v[44:45], v19 offset0:128 offset1:160
	ds_read2_b32 v[46:47], v19 offset0:192 offset1:224
	v_mad_u32_u24 v8, v29, s30, v30
	s_lshl_b32 s31, s30, 4
	s_waitcnt lgkmcnt(4)
	v_cvt_pk_bf16_f32 v32, v32, v33
	v_cvt_pk_bf16_f32 v33, v34, v35
	v_cvt_pk_bf16_f32 v34, v36, v37
	v_cvt_pk_bf16_f32 v35, v38, v39
	global_store_dwordx4 v8, v[32:35], s[44:45]
	v_add_u32_e32 v8, s31, v8
	s_waitcnt lgkmcnt(0)
	v_cvt_pk_bf16_f32 v40, v40, v41
	v_cvt_pk_bf16_f32 v41, v42, v43
	v_cvt_pk_bf16_f32 v42, v44, v45
	v_cvt_pk_bf16_f32 v43, v46, v47
	global_store_dwordx4 v8, v[40:43], s[44:45]
	s_nop 1
.Lxp_dr125:
	s_movk_i32 s19, 126
	s_cmp_ge_u32 s19, s12
	s_cbranch_scc1 .Lxp_dr126
	s_sub_u32 s19, s19, 64
	v_readlane_b32 s44, v104, s19
	v_readlane_b32 s45, v105, s19
	v_readlane_b32 s30, v107, s19
	ds_write_b128 v11, v[48:51] offset:0
	ds_write_b128 v12, v[52:55] offset:1024
	ds_write_b128 v13, v[56:59] offset:2048
	ds_write_b128 v14, v[60:63] offset:3072
	s_waitcnt lgkmcnt(0)
	ds_read2_b32 v[32:33], v18 offset0:0 offset1:32
	ds_read2_b32 v[34:35], v18 offset0:64 offset1:96
	ds_read2_b32 v[36:37], v18 offset0:128 offset1:160
	ds_read2_b32 v[38:39], v18 offset0:192 offset1:224
	ds_read2_b32 v[40:41], v19 offset0:0 offset1:32
	ds_read2_b32 v[42:43], v19 offset0:64 offset1:96
	ds_read2_b32 v[44:45], v19 offset0:128 offset1:160
	ds_read2_b32 v[46:47], v19 offset0:192 offset1:224
	v_mad_u32_u24 v8, v29, s30, v30
	s_lshl_b32 s31, s30, 4
	s_waitcnt lgkmcnt(4)
	v_cvt_pk_bf16_f32 v32, v32, v33
	v_cvt_pk_bf16_f32 v33, v34, v35
	v_cvt_pk_bf16_f32 v34, v36, v37
	v_cvt_pk_bf16_f32 v35, v38, v39
	global_store_dwordx4 v8, v[32:35], s[44:45]
	v_add_u32_e32 v8, s31, v8
	s_waitcnt lgkmcnt(0)
	v_cvt_pk_bf16_f32 v40, v40, v41
	v_cvt_pk_bf16_f32 v41, v42, v43
	v_cvt_pk_bf16_f32 v42, v44, v45
	v_cvt_pk_bf16_f32 v43, v46, v47
	global_store_dwordx4 v8, v[40:43], s[44:45]
	s_nop 1
.Lxp_dr126:
	s_movk_i32 s19, 127
	s_cmp_ge_u32 s19, s12
	s_cbranch_scc1 .Lxp_dr127
	s_sub_u32 s19, s19, 64
	v_readlane_b32 s44, v104, s19
	v_readlane_b32 s45, v105, s19
	v_readlane_b32 s30, v107, s19
	ds_write_b128 v11, v[64:67] offset:0
	ds_write_b128 v12, v[68:71] offset:1024
	ds_write_b128 v13, v[72:75] offset:2048
	ds_write_b128 v14, v[76:79] offset:3072
	s_waitcnt lgkmcnt(0)
	ds_read2_b32 v[32:33], v18 offset0:0 offset1:32
	ds_read2_b32 v[34:35], v18 offset0:64 offset1:96
	ds_read2_b32 v[36:37], v18 offset0:128 offset1:160
	ds_read2_b32 v[38:39], v18 offset0:192 offset1:224
	ds_read2_b32 v[40:41], v19 offset0:0 offset1:32
	ds_read2_b32 v[42:43], v19 offset0:64 offset1:96
	ds_read2_b32 v[44:45], v19 offset0:128 offset1:160
	ds_read2_b32 v[46:47], v19 offset0:192 offset1:224
	v_mad_u32_u24 v8, v29, s30, v30
	s_lshl_b32 s31, s30, 4
	s_waitcnt lgkmcnt(4)
	v_cvt_pk_bf16_f32 v32, v32, v33
	v_cvt_pk_bf16_f32 v33, v34, v35
	v_cvt_pk_bf16_f32 v34, v36, v37
	v_cvt_pk_bf16_f32 v35, v38, v39
	global_store_dwordx4 v8, v[32:35], s[44:45]
	v_add_u32_e32 v8, s31, v8
	s_waitcnt lgkmcnt(0)
	v_cvt_pk_bf16_f32 v40, v40, v41
	v_cvt_pk_bf16_f32 v41, v42, v43
	v_cvt_pk_bf16_f32 v42, v44, v45
	v_cvt_pk_bf16_f32 v43, v46, v47
	global_store_dwordx4 v8, v[40:43], s[44:45]
	s_nop 1
.Lxp_dr127:
	s_waitcnt vmcnt(0)
.LBB0_709:
	v_readlane_b32 s0, v254, 12
	s_add_i32 s18, s0, 5
	s_cmp_lt_i32 s18, s75
	s_cselect_b64 s[4:5], -1, 0
	s_and_b64 s[0:1], s[38:39], s[4:5]
	s_andn2_b64 vcc, exec, s[0:1]
	s_mov_b32 s30, 0x3c800000
	s_cbranch_vccnz .LBB0_777
	s_mov_b64 s[0:1], -1
	s_and_b64 vcc, exec, s[78:79]
	s_cbranch_vccz .LBB0_764
	s_waitcnt vmcnt(0)
	s_waitcnt vmcnt(0) lgkmcnt(0)
	s_barrier
	s_and_saveexec_b64 s[6:7], s[72:73]
	s_cbranch_execz .LBB0_763
	v_readlane_b32 s0, v253, 47
	s_waitcnt vmcnt(0) expcnt(0) lgkmcnt(0)
	s_nop 0
	v_mov_b32_e32 v0, s0
	ds_read_b32 v2, v0
	v_readlane_b32 s0, v253, 48
	s_waitcnt lgkmcnt(0)
	v_cmp_ne_u32_e32 vcc, 0, v2
	v_mov_b32_e32 v0, s0
	ds_read_b32 v0, v0
	s_cbranch_vccnz .LBB0_727
	s_mov_b32 s10, 1
	s_branch .LBB0_715

; #define LAS __attribute__((address_space(3)))
; __global__ void __launch_bounds__(NTHR, 2) mega_fwd(Args A_unused) {
;     extern __shared__ __attribute__((aligned(16))) unsigned char lds_[];
;     cg::grid_group grid = cg::this_grid();
;     LAS unsigned char* lds = (LAS unsigned char*)lds_;
;     const int bid = blockIdx.x, G = gridDim.x;
;     volatile LAS unsigned* xst = (volatile LAS unsigned*)(lds + LDS_BYTES - 64);
	.amdhsa_kernel _Z8mega_fwd4Args
		.amdhsa_group_segment_fixed_size 4096
		.amdhsa_private_segment_fixed_size 0
		.amdhsa_kernarg_size 584
		.amdhsa_user_sgpr_count 2
		.amdhsa_user_sgpr_dispatch_ptr 0
		.amdhsa_user_sgpr_queue_ptr 0
		.amdhsa_user_sgpr_kernarg_segment_ptr 1
		.amdhsa_user_sgpr_dispatch_id 0
		.amdhsa_user_sgpr_kernarg_preload_length 0
		.amdhsa_user_sgpr_kernarg_preload_offset 0
		.amdhsa_user_sgpr_private_segment_size 0
		.amdhsa_uses_dynamic_stack 0
		.amdhsa_enable_private_segment 0
		.amdhsa_system_sgpr_workgroup_id_x 1
		.amdhsa_system_sgpr_workgroup_id_y 0
		.amdhsa_system_sgpr_workgroup_id_z 0
		.amdhsa_system_sgpr_workgroup_info 0
		.amdhsa_system_vgpr_workitem_id 2
		.amdhsa_next_free_vgpr 256
		.amdhsa_next_free_sgpr 100
		.amdhsa_accum_offset 256
		.amdhsa_reserve_vcc 1
		.amdhsa_float_round_mode_32 0
		.amdhsa_float_round_mode_16_64 0
		.amdhsa_float_denorm_mode_32 3
		.amdhsa_float_denorm_mode_16_64 3
		.amdhsa_dx10_clamp 1
		.amdhsa_ieee_mode 1
		.amdhsa_fp16_overflow 0
		.amdhsa_tg_split 0
		.amdhsa_exception_fp_ieee_invalid_op 0
		.amdhsa_exception_fp_denorm_src 0
		.amdhsa_exception_fp_ieee_div_zero 0
		.amdhsa_exception_fp_ieee_overflow 0
		.amdhsa_exception_fp_ieee_underflow 0
		.amdhsa_exception_fp_ieee_inexact 0
		.amdhsa_exception_int_div_zero 0
	.end_amdhsa_kernel

; #define LAS __attribute__((address_space(3)))
; __global__ void __launch_bounds__(NTHR, 2) mega_fwd(Args A_unused) {
;     extern __shared__ __attribute__((aligned(16))) unsigned char lds_[];
;     cg::grid_group grid = cg::this_grid();
;     LAS unsigned char* lds = (LAS unsigned char*)lds_;
;     const int bid = blockIdx.x, G = gridDim.x;
;     volatile LAS unsigned* xst = (volatile LAS unsigned*)(lds + LDS_BYTES - 64);
amdhsa.kernels:
  - .agpr_count:     0
    .args:
      - .offset:         0
        .size:           328
        .value_kind:     by_value
      - .offset:         328
        .size:           4
        .value_kind:     hidden_block_count_x
      - .offset:         332
        .size:           4
        .value_kind:     hidden_block_count_y
      - .offset:         336
        .size:           4
        .value_kind:     hidden_block_count_z
      - .offset:         340
        .size:           2
        .value_kind:     hidden_group_size_x
      - .offset:         342
        .size:           2
        .value_kind:     hidden_group_size_y
      - .offset:         344
        .size:           2
        .value_kind:     hidden_group_size_z
      - .offset:         346
        .size:           2
        .value_kind:     hidden_remainder_x
      - .offset:         348
        .size:           2
        .value_kind:     hidden_remainder_y
      - .offset:         350
        .size:           2
        .value_kind:     hidden_remainder_z
      - .offset:         368
        .size:           8
        .value_kind:     hidden_global_offset_x
      - .offset:         376
        .size:           8
        .value_kind:     hidden_global_offset_y
      - .offset:         384
        .size:           8
        .value_kind:     hidden_global_offset_z
      - .offset:         392
        .size:           2
        .value_kind:     hidden_grid_dims
      - .offset:         416
        .size:           8
        .value_kind:     hidden_multigrid_sync_arg
      - .offset:         448
        .size:           4
        .value_kind:     hidden_dynamic_lds_size
    .group_segment_fixed_size: 4096
    .kernarg_segment_align: 8
    .kernarg_segment_size: 584
    .language:       OpenCL C
    .language_version:
      - 2
      - 0
    .max_flat_workgroup_size: 512
    .name:           _Z8mega_fwd4Args
    .private_segment_fixed_size: 0
    .sgpr_count:     106
    .sgpr_spill_count: 330
    .symbol:         _Z8mega_fwd4Args.kd
    .uniform_work_group_size: 1
    .uses_dynamic_stack: false
    .vgpr_count:     256
    .vgpr_spill_count: 0
    .wavefront_size: 64
